# P7 start stagger in 32 groups (bi) x s_sleep 32
# baseline (speedup 1.0000x reference)
.LBB0_295:
	s_nop 0
	v_readlane_b32 s0, v254, 37
	v_readlane_b32 s1, v254, 38
	s_and_b64 vcc, exec, s[0:1]
	s_cbranch_vccz .LBB0_316
	s_mov_b32 s36, s35
	s_mov_b32 s0, s98
	s_mov_b32 s1, -1
	v_mbcnt_lo_u32_b32 v0, -1, 0
	v_mbcnt_hi_u32_b32 v0, s1, v0
	v_readlane_b32 s1, v252, 0
	v_lshl_add_u32 v158, s0, 6, v0
	s_mov_b32 s4, s1
	s_ashr_i32 s0, s1, 3
	v_readlane_b32 s5, v254, 6
	s_cmp_ge_i32 s0, s5
	s_cbranch_scc1 .LBB0_315
	s_cmpk_gt_i32 s0, 0x9f
	s_cbranch_scc1 .LBB0_315
	s_and_b32 s6, s0, 31
.Lp7_stag_loop:
	s_cmp_eq_u32 s6, 0
	s_cbranch_scc1 .Lp7_nostag
	s_sleep 32
	s_add_i32 s6, s6, -1
	s_branch .Lp7_stag_loop
